# P1 GEMM epilogue: the 16 store addresses stepped with 64-bit adds from the first one instead of recomputed per store on both layout paths
# speedup vs baseline: 1.0194x; 1.0194x over previous
.LBB0_132:
	s_mov_b32 s98, 0x80000
	s_movk_i32 s100, 0x400
	s_cmp_lg_u32 s69, 0
	s_cbranch_scc1 .Le1_steps
	s_movk_i32 s98, 0x100
	s_mov_b32 s100, 0x18000
.Le1_steps:
	s_mov_b32 s99, 0
	s_mov_b32 s101, 0
	v_mov_b64_e32 v[154:155], v[156:157]
	v_cvt_pk_bf16_f32 v126, v126, v127
	v_cvt_pk_bf16_f32 v127, v128, v129
	v_cvt_pk_bf16_f32 v128, v122, v123
	v_cvt_pk_bf16_f32 v129, v124, v125
	global_store_dwordx4 v[154:155], v[126:129], off sc1
	v_cvt_pk_bf16_f32 v118, v118, v119
	v_cvt_pk_bf16_f32 v119, v120, v121
	v_cvt_pk_bf16_f32 v120, v114, v115
	v_cvt_pk_bf16_f32 v121, v116, v117
	v_lshl_add_u64 v[152:153], s[98:99], 0, v[154:155]
	global_store_dwordx4 v[152:153], v[118:121], off sc1
	v_lshl_add_u64 v[154:155], s[100:101], 0, v[154:155]
	v_cvt_pk_bf16_f32 v110, v110, v111
	v_cvt_pk_bf16_f32 v111, v112, v113
	v_cvt_pk_bf16_f32 v112, v106, v107
	v_cvt_pk_bf16_f32 v113, v108, v109
	global_store_dwordx4 v[154:155], v[110:113], off sc1
	v_cvt_pk_bf16_f32 v102, v102, v103
	v_cvt_pk_bf16_f32 v103, v104, v105
	v_cvt_pk_bf16_f32 v104, v98, v99
	v_cvt_pk_bf16_f32 v105, v100, v101
	v_lshl_add_u64 v[152:153], s[98:99], 0, v[154:155]
	global_store_dwordx4 v[152:153], v[102:105], off sc1
	v_lshl_add_u64 v[154:155], s[100:101], 0, v[154:155]
	v_cvt_pk_bf16_f32 v94, v94, v95
	v_cvt_pk_bf16_f32 v95, v96, v97
	v_cvt_pk_bf16_f32 v96, v90, v91
	v_cvt_pk_bf16_f32 v97, v92, v93
	global_store_dwordx4 v[154:155], v[94:97], off sc1
	v_cvt_pk_bf16_f32 v86, v86, v87
	v_cvt_pk_bf16_f32 v87, v88, v89
	v_cvt_pk_bf16_f32 v88, v82, v83
	v_cvt_pk_bf16_f32 v89, v84, v85
	v_lshl_add_u64 v[152:153], s[98:99], 0, v[154:155]
	global_store_dwordx4 v[152:153], v[86:89], off sc1
	v_lshl_add_u64 v[154:155], s[100:101], 0, v[154:155]
	v_cvt_pk_bf16_f32 v78, v78, v79
	v_cvt_pk_bf16_f32 v79, v80, v81
	v_cvt_pk_bf16_f32 v80, v74, v75
	v_cvt_pk_bf16_f32 v81, v76, v77
	global_store_dwordx4 v[154:155], v[78:81], off sc1
	v_cvt_pk_bf16_f32 v70, v70, v71
	v_cvt_pk_bf16_f32 v71, v72, v73
	v_cvt_pk_bf16_f32 v72, v66, v67
	v_cvt_pk_bf16_f32 v73, v68, v69
	v_lshl_add_u64 v[152:153], s[98:99], 0, v[154:155]
	global_store_dwordx4 v[152:153], v[70:73], off sc1
	v_lshl_add_u64 v[154:155], s[100:101], 3, v[156:157]
	v_cvt_pk_bf16_f32 v62, v62, v63
	v_cvt_pk_bf16_f32 v63, v64, v65
	v_cvt_pk_bf16_f32 v64, v58, v59
	v_cvt_pk_bf16_f32 v65, v60, v61
	global_store_dwordx4 v[154:155], v[62:65], off sc1
	v_cvt_pk_bf16_f32 v54, v54, v55
	v_cvt_pk_bf16_f32 v55, v56, v57
	v_cvt_pk_bf16_f32 v56, v50, v51
	v_cvt_pk_bf16_f32 v57, v52, v53
	v_lshl_add_u64 v[152:153], s[98:99], 0, v[154:155]
	global_store_dwordx4 v[152:153], v[54:57], off sc1
	v_lshl_add_u64 v[154:155], s[100:101], 0, v[154:155]
	v_cvt_pk_bf16_f32 v46, v46, v47
	v_cvt_pk_bf16_f32 v47, v48, v49
	v_cvt_pk_bf16_f32 v48, v42, v43
	v_cvt_pk_bf16_f32 v49, v44, v45
	global_store_dwordx4 v[154:155], v[46:49], off sc1
	v_cvt_pk_bf16_f32 v38, v38, v39
	v_cvt_pk_bf16_f32 v39, v40, v41
	v_cvt_pk_bf16_f32 v40, v34, v35
	v_cvt_pk_bf16_f32 v41, v36, v37
	v_lshl_add_u64 v[152:153], s[98:99], 0, v[154:155]
	global_store_dwordx4 v[152:153], v[38:41], off sc1
	v_lshl_add_u64 v[154:155], s[100:101], 0, v[154:155]
	v_cvt_pk_bf16_f32 v30, v30, v31
	v_cvt_pk_bf16_f32 v31, v32, v33
	v_cvt_pk_bf16_f32 v32, v26, v27
	v_cvt_pk_bf16_f32 v33, v28, v29
	global_store_dwordx4 v[154:155], v[30:33], off sc1
	v_cvt_pk_bf16_f32 v22, v22, v23
	v_cvt_pk_bf16_f32 v23, v24, v25
	v_cvt_pk_bf16_f32 v24, v18, v19
	v_cvt_pk_bf16_f32 v25, v20, v21
	v_lshl_add_u64 v[152:153], s[98:99], 0, v[154:155]
	global_store_dwordx4 v[152:153], v[22:25], off sc1
	v_lshl_add_u64 v[154:155], s[100:101], 0, v[154:155]
	v_cvt_pk_bf16_f32 v14, v14, v15
	v_cvt_pk_bf16_f32 v15, v16, v17
	v_cvt_pk_bf16_f32 v16, v10, v11
	v_cvt_pk_bf16_f32 v17, v12, v13
	global_store_dwordx4 v[154:155], v[14:17], off sc1
	v_cvt_pk_bf16_f32 v6, v6, v7
	v_cvt_pk_bf16_f32 v7, v8, v9
	v_cvt_pk_bf16_f32 v8, v2, v3
	v_cvt_pk_bf16_f32 v9, v4, v5
	v_lshl_add_u64 v[152:153], s[98:99], 0, v[154:155]
	s_andn2_b64 vcc, exec, s[28:29]
	s_mov_b64 s[4:5], -1
	global_store_dwordx4 v[152:153], v[6:9], off sc1
	s_cbranch_vccnz .LBB0_120
	s_andn2_b64 vcc, exec, s[10:11]
	s_cbranch_vccnz .LBB0_119
	s_barrier
	s_branch .LBB0_119
.LBB0_180:
	v_ashrrev_i32_e32 v149, 31, v148
	s_branch .LBB0_131
.LBB0_196:
	s_waitcnt vmcnt(0)
	s_barrier
